# mixer item loops: parameter re-fetch at each item start no longer drains the previous item's stores (vmcnt(0) removed; only LDS reads follow)
# speedup vs baseline: 1.0088x; 1.0008x over previous
; __device__ __forceinline__ int opaque_bid() { int t = blockIdx.x; asm volatile("" : "+s"(t)); return t; }
; __device__ __forceinline__ int opaque_gd() { int t = gridDim.x; asm volatile("" : "+s"(t)); return t; }
; __device__ __forceinline__ int opaque_tid() { int t = threadIdx.x; asm volatile("" : "+v"(t)); return t; }
; __device__ __forceinline__ Params fetchP(const LAS Params* lp0) { unsigned la = (unsigned)(unsigned long long)lp0; asm volatile("" : "+v"(la)); const LAS Params* lp = (const LAS Params*)la; Params q; PFIELDS(PFETCH) q.ph_lo = 0; q.ph_hi = 0; return q; }
; __device__ __forceinline__ void lru_fix_item(const Params& p, int l, int item) {
;     const int tid = opaque_tid(), wid = tid >> 6, lane = tid & 63;
;     const int b = item >> 6, h = (item >> 4) & 3, seg = item & 15;
;     const int t0 = seg * 128 + wid * 16; const size_t Tb = (size_t)b * SEQ;
;     const int ch = h * 64 + lane;
;     const float* sc = (const float*)p.hbuf + ((((size_t)b * 4 + h) * 16 + seg) * 8 + wid) * 2048 + lane * 16;
;     f32x4 hv[4], av[4]; unsigned gr[16];
; #pragma unroll
;     for (int q = 0; q < 4; ++q) { hv[q] = *(const f32x4*)(sc + q * 4); av[q] = *(const f32x4*)(sc + 1024 + q * 4); }
; #pragma unroll
;     for (int i = 0; i < 16; ++i) gr[i] = p.z[(Tb + t0 + i) * ZLD + 2560 + ch];
;     const float* car = p.lru_carry + (((size_t)b * 4 + h) * 16) * 128;
;     float Hin = 0.f;
; #pragma unroll 4
;     for (int s = 0; s < seg; ++s) { const float as = car[s * 128 + lane * 2], hs = car[s * 128 + lane * 2 + 1]; Hin = as * Hin + hs; }
; __device__ __forceinline__ void run_phase(const LAS Params* lp, int ph, LAS unsigned char* lds) {
;     ...
;     case 2: for (int it = opaque_bid(); it < 1280; it += opaque_gd()) { const Params p = fetchP(lp); const int jx = (it & ~255) + (it & 7) * 32 + ((it & 255) >> 3);
;             if (it < 256) hgrn_item(p, l, jx, 1, lds); else if (it < 768) gmlp_item(p, l, jx - 256, lds); else lru_fix_item(p, l, jx - 768); } break;
.LBB0_307:
	v_mov_b32_e32 v0, s84
	ds_read2_b64 v[4:7], v0 offset0:8 offset1:9
	ds_read2_b64 v[8:11], v0 offset0:29 offset1:30
	s_lshl_b32 s7, s72, 5
	s_and_b32 s6, s72, 0xffffff00
	s_and_b32 s7, s7, 0xe0
	s_waitcnt lgkmcnt(0)
	v_readfirstlane_b32 s2, v4
	v_readfirstlane_b32 s20, v5
	v_readfirstlane_b32 s23, v6
	v_readfirstlane_b32 s36, v7
	ds_read2_b64 v[4:7], v0 offset0:11 offset1:31
	s_or_b32 s21, s7, s6
	v_readfirstlane_b32 s34, v8
	v_readfirstlane_b32 s35, v9
	v_readfirstlane_b32 s9, v10
	s_waitcnt lgkmcnt(0)
	v_readfirstlane_b32 s0, v4
	v_readfirstlane_b32 s14, v5
	v_readfirstlane_b32 s30, v6
	v_readfirstlane_b32 s31, v7
	ds_read2_b64 v[4:7], v0 offset0:33 offset1:37
	v_readfirstlane_b32 s33, v11
	s_mov_b64 s[6:7], -1
	s_cmpk_gt_i32 s72, 0xff
	s_waitcnt lgkmcnt(0)
	v_readfirstlane_b32 s4, v4
	v_readfirstlane_b32 s5, v5
	v_readfirstlane_b32 s18, v6
	v_readfirstlane_b32 s19, v7
	ds_read2_b64 v[4:7], v0 offset0:39 offset1:40
	ds_read_b64 v[0:1], v0 offset:328
	s_waitcnt lgkmcnt(1)
	v_readfirstlane_b32 s15, v4
	v_readfirstlane_b32 s17, v5
	v_readfirstlane_b32 s10, v6
	v_readfirstlane_b32 s11, v7
	s_waitcnt lgkmcnt(0)
	v_readfirstlane_b32 s12, v0
	v_readfirstlane_b32 s13, v1
	s_cbranch_scc0 .LBB0_326
	s_bfe_u32 s6, s72, 0x50003
	s_or_b32 s16, s21, s6
	s_cmpk_gt_u32 s72, 0x2ff
	s_mov_b64 s[6:7], -1
	s_cbranch_scc0 .LBB0_319
	s_add_i32 s6, s21, 0xfffffd00
	s_ashr_i32 s38, s6, 6
	s_bfe_u32 s37, s16, 0x20004
	s_ashr_i32 s39, s38, 31
	s_lshl_b64 s[6:7], s[38:39], 6
	s_lshl_b32 s8, s37, 4
	s_bfe_u32 s22, s72, 0x40003
	s_or_b32 s8, s6, s8
	s_or_b32 s6, s8, s22
	v_mov_b32_e32 v1, v202
	s_lshl_b64 s[40:41], s[6:7], 16
	s_add_u32 s40, s9, s40
	v_ashrrev_i32_e32 v0, 6, v1
	v_and_b32_e32 v36, 63, v1
	v_ashrrev_i32_e32 v1, 31, v0
	s_addc_u32 s41, s33, s41
	s_lshl_b32 s6, s22, 7
	v_lshlrev_b64 v[4:5], 13, v[0:1]
	v_lshl_add_u32 v0, v0, 4, s6
	s_lshl_b64 s[38:39], s[38:39], 11
	v_ashrrev_i32_e32 v1, 31, v0
	v_lshl_add_u64 v[4:5], s[40:41], 0, v[4:5]
	v_lshlrev_b32_e32 v6, 6, v36
	v_mov_b32_e32 v7, v2
	v_lshl_add_u64 v[38:39], s[38:39], 0, v[0:1]
	v_mov_b64_e32 v[0:1], s[34:35]
	s_movk_i32 s6, 0x1600
	v_lshl_add_u64 v[8:9], v[4:5], 0, v[6:7]
	s_mov_b64 s[40:41], 0x1000
	v_lshl_or_b32 v3, s37, 6, v36
	v_mad_u64_u32 v[40:41], s[38:39], v38, s6, v[0:1]
	v_lshl_add_u64 v[24:25], v[8:9], 0, s[40:41]
	global_load_dwordx4 v[4:7], v[8:9], off offset:48
	global_load_dwordx4 v[12:15], v[8:9], off offset:32
	global_load_dwordx4 v[20:23], v[8:9], off offset:16
	global_load_dwordx4 v[28:31], v[8:9], off
	v_add_co_u32_e32 v8, vcc, s80, v8
	v_mad_i32_i24 v41, v39, s6, v41
	v_lshlrev_b32_e32 v0, 1, v3
	v_mov_b32_e32 v1, v2
	v_addc_co_u32_e32 v9, vcc, 0, v9, vcc
	v_lshl_add_u64 v[40:41], v[40:41], 0, v[0:1]
	v_add_co_u32_e32 v42, vcc, s80, v40
	global_load_dwordx4 v[32:35], v[8:9], off
	s_nop 0
	global_load_dwordx4 v[8:11], v[24:25], off offset:48
	global_load_dwordx4 v[16:19], v[24:25], off offset:32
	s_nop 0
	global_load_dwordx4 v[24:27], v[24:25], off offset:16
	v_addc_co_u32_e32 v43, vcc, 0, v41, vcc
	global_load_ushort v1, v[42:43], off offset:1024
	v_add_co_u32_e32 v42, vcc, s81, v40
	s_movk_i32 s6, 0x4000
	s_nop 0
	v_addc_co_u32_e32 v43, vcc, 0, v41, vcc
	global_load_ushort v55, v[42:43], off offset:2560
	v_add_co_u32_e32 v42, vcc, s6, v40
	s_movk_i32 s6, 0x5000
	s_nop 0
	v_addc_co_u32_e32 v43, vcc, 0, v41, vcc
	global_load_ushort v54, v[42:43], off
	v_add_co_u32_e32 v42, vcc, s6, v40
	s_movk_i32 s6, 0x6000
	s_nop 0
	v_addc_co_u32_e32 v43, vcc, 0, v41, vcc
	global_load_ushort v53, v[42:43], off offset:1536
	v_add_co_u32_e32 v42, vcc, s6, v40
	s_mov_b32 s6, 0x8000
	s_nop 0
	v_addc_co_u32_e32 v43, vcc, 0, v41, vcc
	global_load_ushort v52, v[42:43], off offset:3072
	v_add_co_u32_e32 v42, vcc, s6, v40
	s_mov_b32 s6, 0x9000
	s_nop 0
	v_addc_co_u32_e32 v43, vcc, 0, v41, vcc
	global_load_ushort v51, v[42:43], off offset:512
	v_add_co_u32_e32 v42, vcc, s6, v40
	s_mov_b32 s6, 0xa000
	s_nop 0
	v_addc_co_u32_e32 v43, vcc, 0, v41, vcc
	global_load_ushort v50, v[42:43], off offset:2048
	v_add_co_u32_e32 v42, vcc, s6, v40
	s_mov_b32 s6, 0xc000
	s_nop 0
	v_addc_co_u32_e32 v43, vcc, 0, v41, vcc
	global_load_ushort v49, v[42:43], off offset:3584
	v_add_co_u32_e32 v42, vcc, s6, v40
	s_mov_b32 s6, 0xd000
	s_nop 0
	v_addc_co_u32_e32 v43, vcc, 0, v41, vcc
	global_load_ushort v48, v[42:43], off offset:1024
	v_add_co_u32_e32 v42, vcc, s6, v40
	s_mov_b32 s6, 0xf000
	s_nop 0
	v_addc_co_u32_e32 v43, vcc, 0, v41, vcc
	global_load_ushort v47, v[42:43], off offset:2560
	v_add_co_u32_e32 v42, vcc, s6, v40
	s_mov_b32 s6, 0x10000
	s_nop 0
	v_addc_co_u32_e32 v43, vcc, 0, v41, vcc
	global_load_ushort v46, v[42:43], off
	v_add_co_u32_e32 v42, vcc, s6, v40
	s_cmp_eq_u32 s22, 0
	s_nop 0
	v_addc_co_u32_e32 v43, vcc, 0, v41, vcc
	global_load_ushort v45, v[42:43], off offset:1536
	v_add_co_u32_e32 v42, vcc, 0x11000, v40
	s_nop 1
	v_addc_co_u32_e32 v43, vcc, 0, v41, vcc
	global_load_ushort v44, v[42:43], off offset:3072
	v_add_co_u32_e32 v42, vcc, 0x13000, v40
	s_nop 1
	v_addc_co_u32_e32 v43, vcc, 0, v41, vcc
	v_add_co_u32_e32 v56, vcc, 0x14000, v40
	global_load_ushort v43, v[42:43], off offset:512
	s_nop 0
	v_addc_co_u32_e32 v57, vcc, 0, v41, vcc
	v_add_co_u32_e32 v40, vcc, 0x15000, v40
	global_load_ushort v42, v[56:57], off offset:2048
	s_nop 0
	v_addc_co_u32_e32 v41, vcc, 0, v41, vcc
	global_load_ushort v3, v[40:41], off offset:3584
	s_cbranch_scc1 .LBB0_314
	s_mov_b32 s9, s7
	s_lshl_b64 s[6:7], s[8:9], 9
	s_add_u32 s6, s15, s6
	s_addc_u32 s7, s17, s7
	s_cmp_lt_u32 s22, 4
	v_lshlrev_b32_e32 v56, 1, v36
	s_mov_b32 s38, 0x16000
	s_cbranch_scc1 .LBB0_315
	s_lshr_b32 s8, s72, 3
	s_and_b32 s8, s8, 12
	s_mov_b32 s9, 0
	v_mov_b32_e32 v37, 0
	v_mov_b32_e32 v40, v56

; #define LAS __attribute__((address_space(3)))
; __device__ __forceinline__ void lds_barrier() { asm volatile("s_waitcnt lgkmcnt(0)" ::: "memory"); __builtin_amdgcn_s_barrier(); asm volatile("" ::: "memory"); }
; __device__ __forceinline__ int opaque_bid() { int t = blockIdx.x; asm volatile("" : "+s"(t)); return t; }
; __device__ __forceinline__ int opaque_gd() { int t = gridDim.x; asm volatile("" : "+s"(t)); return t; }
; __device__ __forceinline__ int opaque_tid() { int t = threadIdx.x; asm volatile("" : "+v"(t)); return t; }
; __device__ __forceinline__ Params fetchP(const LAS Params* lp0) { unsigned la = (unsigned)(unsigned long long)lp0; asm volatile("" : "+v"(la)); const LAS Params* lp = (const LAS Params*)la; Params q; PFIELDS(PFETCH) q.ph_lo = 0; q.ph_hi = 0; return q; }
; __device__ __forceinline__ void lru_item(const Params& p, int l, int item, LAS unsigned char* lds) {
;     const int tid = opaque_tid(), wid = tid >> 6, lane = tid & 63, fr = lane & 15, fq = lane >> 4;
;     const int b = item >> 6, h = (item >> 4) & 3, seg = item & 15;
;     LAS unsigned char* wb = lds + wid * 10752;
;     LAS bf16_t* xa = (LAS bf16_t*)wb; LAS float* xf = (LAS float*)(wb + 2304); LAS float* sa = (LAS float*)(wb + 6528);
;     LAS float* ct = (LAS float*)(lds + 86016);
;     const int t0 = seg * 128 + wid * 16; const size_t Tb = (size_t)b * SEQ;
;     const int ch = h * 64 + lane;
;     lds_barrier();
;     unsigned xr[19];
; #pragma unroll
;     for (int i = 0; i < 19; ++i) { const int t = t0 - 3 + i; xr[i] = (t >= 0) ? (unsigned)p.z[(Tb + (t >= 0 ? t : 0)) * ZLD + 2304 + ch] : 0u; }
; __device__ __forceinline__ void run_phase(const LAS Params* lp, int ph, LAS unsigned char* lds) {
;     ...
;     case 1: for (int it = opaque_bid(); it < 1280; it += opaque_gd()) { const Params p = fetchP(lp); const int jx = (it & ~255) + (it & 7) * 32 + ((it & 255) >> 3);
;             if (it < 256) hgrn_item(p, l, jx, 0, lds); else if (it < 768) attn_item(p, l, jx - 256, lds); else lru_item(p, l, jx - 768, lds); } break;
.LBB0_353:
	v_mov_b32_e32 v0, s84
	ds_read2_b64 v[4:7], v0 offset0:6 offset1:15
	ds_read2_b64 v[8:11], v0 offset0:12 offset1:13
	s_lshl_b32 s0, s2, 5
	s_and_b32 s39, s2, 0xffffff00
	s_and_b32 s95, s0, 0xe0
	s_waitcnt lgkmcnt(0)
	v_readfirstlane_b32 s26, v4
	v_readfirstlane_b32 s27, v5
	v_readfirstlane_b32 s30, v6
	v_readfirstlane_b32 s31, v7
	ds_read2_b64 v[4:7], v0 offset0:17 offset1:31
	s_or_b32 s69, s95, s39
	s_mov_b64 s[4:5], -1
	s_cmpk_gt_i32 s2, 0xff
	s_waitcnt lgkmcnt(0)
	v_readfirstlane_b32 s6, v4
	v_readfirstlane_b32 s7, v5
	v_readfirstlane_b32 s10, v6
	v_readfirstlane_b32 s11, v7
	ds_read2_b64 v[4:7], v0 offset0:34 offset1:35
	v_readfirstlane_b32 s33, v8
	v_readfirstlane_b32 s44, v9
	v_readfirstlane_b32 s17, v10
	v_readfirstlane_b32 s22, v11
	ds_read2_b64 v[8:11], v0 offset0:29 offset1:30
	s_waitcnt lgkmcnt(1)
	v_readfirstlane_b32 s70, v4
	v_readfirstlane_b32 s71, v5
	v_readfirstlane_b32 s36, v6
	v_readfirstlane_b32 s37, v7
	ds_read2_b64 v[4:7], v0 offset0:37 offset1:38
	s_waitcnt lgkmcnt(1)
	v_readfirstlane_b32 s8, v8
	v_readfirstlane_b32 s9, v9
	v_readfirstlane_b32 s15, v10
	v_readfirstlane_b32 s94, v11
	s_waitcnt lgkmcnt(0)
	v_readfirstlane_b32 s23, v4
	v_readfirstlane_b32 s97, v5
	v_readfirstlane_b32 s34, v6
	v_readfirstlane_b32 s35, v7
	ds_read2_b64 v[4:7], v0 offset0:39 offset1:40
	ds_read_b64 v[0:1], v0 offset:328
	s_waitcnt lgkmcnt(1)
	v_readfirstlane_b32 s41, v4
	v_readfirstlane_b32 s14, v5
	v_readfirstlane_b32 s20, v6
	v_readfirstlane_b32 s21, v7
	s_waitcnt lgkmcnt(0)
	v_readfirstlane_b32 s18, v0
	v_readfirstlane_b32 s19, v1
	s_cbranch_scc0 .LBB0_415
	s_bfe_u32 s96, s2, 0x50003
	s_or_b32 s42, s69, s96
	s_cmpk_gt_u32 s2, 0x2ff
	s_cbranch_scc0 .LBB0_400
	s_add_i32 s4, s69, 0xfffffd00
	v_mov_b32_e32 v1, v202
	s_bfe_u32 s38, s42, 0x20004
	s_bfe_u32 s79, s2, 0x40003
	s_ashr_i32 s28, s4, 6
	v_ashrrev_i32_e32 v0, 6, v1
	v_and_b32_e32 v3, 63, v1
	s_lshl_b32 s4, s79, 7
	s_lshl_b32 s16, s38, 6
	s_waitcnt lgkmcnt(0)
	s_barrier
	v_lshl_add_u32 v76, v0, 4, s4
	s_ashr_i32 s29, s28, 31
	v_or_b32_e32 v78, s16, v3
	s_lshl_b64 s[72:73], s[28:29], 11
	v_cmp_lt_i32_e32 vcc, 2, v76
	v_mov_b32_e32 v87, 0
	v_lshlrev_b32_e32 v4, 1, v78
	v_mov_b32_e32 v88, 0
	s_and_saveexec_b64 s[4:5], vcc
	s_cbranch_execz .LBB0_357
	v_add_u32_e32 v6, -3, v76
	v_mov_b32_e32 v7, v2
	v_lshl_add_u64 v[6:7], s[72:73], 0, v[6:7]
	v_mov_b64_e32 v[8:9], s[8:9]
	s_movk_i32 s45, 0x1600
	v_mad_u64_u32 v[8:9], s[74:75], v6, s45, v[8:9]
	v_mad_i32_i24 v9, v7, s45, v9
	v_mov_b32_e32 v5, v2
	v_lshl_add_u64 v[6:7], v[8:9], 0, v[4:5]
	v_add_co_u32_e32 v6, vcc, 0x1000, v6
	s_nop 1
	v_addc_co_u32_e32 v7, vcc, 0, v7, vcc
	global_load_ushort v5, v[6:7], off offset:512
	s_waitcnt vmcnt(0)
	v_lshlrev_b32_e32 v88, 16, v5
